# MLA attention loop: K-side software pipelining (landing wait, barrier, K reads of tile k+1 and DMA of tile k+2 before the 2nd PV batch)
# baseline (speedup 1.0000x reference)
.LBB0_121:
	s_lshl_b32 s28, s24, 8
	s_lshl_b32 s0, s25, 7
	s_add_i32 s0, s0, s28
	s_cmp_lt_u32 s24, 4
	s_cselect_b32 s41, 4, 0x44
	s_andn2_b64 vcc, exec, s[30:31]
	s_mov_b64 s[30:31], -1
	s_cbranch_vccz .LBB0_125
	s_mul_i32 s25, s0, 0x600
	v_readlane_b32 s30, v253, 3
	s_mul_hi_i32 s1, s0, 0x600
	v_readlane_b32 s31, v253, 4
	s_add_u32 s25, s30, s25
	s_mul_i32 s30, s40, 0x60
	s_addc_u32 s1, s31, s1
	s_ashr_i32 s31, s30, 31
	s_lshl_b64 s[30:31], s[30:31], 1
	s_add_u32 s42, s25, s30
	s_addc_u32 s43, s1, s31
	s_mul_i32 s25, s28, 0x600
	v_readlane_b32 s26, v253, 5
	s_mul_hi_u32 s1, s28, 0x600
	s_add_u32 s25, s26, s25
	v_readlane_b32 s26, v253, 6
	s_addc_u32 s1, s26, s1
	s_add_u32 s36, s25, s30
	s_addc_u32 s37, s1, s31
	s_lshl_b64 s[30:31], s[28:29], 11
	s_add_u32 s1, s82, s30
	s_addc_u32 s25, s83, s31
	s_lshl_b32 s30, s40, 6
	s_ashr_i32 s31, s30, 31
	s_lshl_b64 s[30:31], s[30:31], 1
	v_mov_b32_e32 v74, v208
	v_mov_b32_e32 v75, v208
	s_add_u32 s1, s1, s30
	v_mov_b32_e32 v26, v208
	s_addc_u32 s25, s25, s31
	s_add_u32 s38, s1, 0x9f54400
	v_ashrrev_i32_e32 v25, 6, v26
	v_and_b32_e32 v27, 15, v26
	v_and_b32_e32 v128, 48, v26
	v_lshl_or_b32 v12, v25, 5, v27
	v_lshl_add_u64 v[8:9], s[42:43], 0, v[128:129]
	s_movk_i32 s1, 0x600
	v_mad_i64_i32 v[10:11], s[42:43], v12, s1, v[8:9]
	v_or_b32_e32 v12, 16, v12
	v_mad_i64_i32 v[20:21], s[42:43], v12, s1, v[8:9]
	s_mov_b32 s1, 0x2aaaaaab
	v_mul_hi_i32 v29, v26, s1
	v_lshrrev_b32_e32 v30, 31, v29
	v_ashrrev_i32_e32 v29, 1, v29
	v_and_b32_e32 v28, 0xffffffc0, v26
	v_add_u32_e32 v29, v29, v30
	v_and_b32_e32 v24, 63, v26
	v_mul_lo_u32 v30, v29, 12
	v_add_u32_e32 v28, 0x100, v28
	v_sub_u32_e32 v30, v26, v30
	v_lshrrev_b32_e32 v31, 2, v29
	v_or_b32_e32 v24, v28, v24
	v_bitop3_b32 v30, v31, v30, 3 bitop3:0x6c
	v_mul_hi_i32 v31, v24, s1
	v_lshrrev_b32_e32 v32, 31, v31
	v_ashrrev_i32_e32 v31, 1, v31
	v_add_u32_e32 v31, v31, v32
	v_mul_lo_u32 v32, v31, 12
	v_sub_u32_e32 v32, v24, v32
	v_lshrrev_b32_e32 v33, 2, v31
	v_bitop3_b32 v32, v33, v32, 3 bitop3:0x6c
	v_bitop3_b32 v33, v26, 63, v213 bitop3:0xe0
	v_add_u32_e32 v33, 0x200, v33
	v_mul_hi_i32 v34, v33, s1
	v_lshrrev_b32_e32 v35, 31, v34
	v_ashrrev_i32_e32 v34, 1, v34
	v_add_u32_e32 v34, v34, v35
	v_mul_lo_u32 v35, v34, 12
	v_sub_u32_e32 v33, v33, v35
	v_lshrrev_b32_e32 v35, 2, v34
	v_bitop3_b32 v33, v35, v33, 3 bitop3:0x6c
	v_ashrrev_i32_e32 v35, 31, v26
	v_lshrrev_b32_e32 v35, 29, v35
	v_add_u32_e32 v35, v26, v35
	v_ashrrev_i32_e32 v28, 31, v28
	v_ashrrev_i32_e32 v36, 3, v35
	v_and_b32_e32 v35, 0x1ffffff8, v35
	v_lshrrev_b32_e32 v28, 29, v28
	v_sub_u32_e32 v35, v26, v35
	v_lshrrev_b32_e32 v37, 1, v36
	v_add_u32_e32 v28, v24, v28
	v_bitop3_b32 v35, v37, v35, 7 bitop3:0x6c
	v_ashrrev_i32_e32 v37, 3, v28
	v_and_b32_e32 v28, 0x1ffffff8, v28
	v_sub_u32_e32 v24, v24, v28
	v_lshrrev_b32_e32 v28, 1, v37
	v_bitop3_b32 v24, v28, v24, 7 bitop3:0x6c
	v_lshlrev_b32_e32 v28, 10, v37
	s_movk_i32 s1, 0x300
	v_lshl_add_u32 v64, v24, 3, v28
	v_mul_lo_u32 v24, v29, s1
	v_lshl_add_u32 v66, v30, 3, v24
	v_mul_lo_u32 v24, v31, s1
	v_lshl_add_u32 v68, v32, 3, v24
	v_mul_lo_u32 v24, v34, s1
	v_lshlrev_b32_e32 v76, 10, v25
	v_lshl_add_u32 v70, v33, 3, v24
	v_lshlrev_b32_e32 v24, 10, v36
	v_ashrrev_i32_e32 v67, 31, v66
	v_readfirstlane_b32 s1, v76
	v_add_u32_e32 v28, 0x1000, v76
	global_load_dwordx4 v[0:3], v[10:11], off
	global_load_dwordx4 v[4:7], v[10:11], off offset:64
	s_nop 0
	global_load_dwordx4 v[8:11], v[10:11], off offset:128
	s_nop 0
	global_load_dwordx4 v[12:15], v[20:21], off
	global_load_dwordx4 v[16:19], v[20:21], off offset:64
	s_nop 0
	global_load_dwordx4 v[20:23], v[20:21], off offset:128
	v_lshl_add_u32 v72, v35, 3, v24
	s_waitcnt lgkmcnt(0)
	s_barrier
	v_lshl_add_u64 v[24:25], v[66:67], 1, s[36:37]
	s_mov_b32 m0, s1
	v_ashrrev_i32_e32 v69, 31, v68
	v_readfirstlane_b32 s1, v28
	v_add_u32_e32 v28, 0x2000, v76
	global_load_lds_dwordx4 v[24:25], off
	v_lshl_add_u64 v[24:25], v[68:69], 1, s[36:37]
	s_mov_b32 m0, s1
	v_ashrrev_i32_e32 v71, 31, v70
	v_readfirstlane_b32 s1, v28
	v_add_u32_e32 v28, 0x3000, v76
	s_addc_u32 s39, s25, 0
	global_load_lds_dwordx4 v[24:25], off
	v_lshl_add_u64 v[24:25], v[70:71], 1, s[36:37]
	s_mov_b32 m0, s1
	v_ashrrev_i32_e32 v73, 31, v72
	v_readfirstlane_b32 s1, v28
	v_add_u32_e32 v28, 0x4000, v76
	global_load_lds_dwordx4 v[24:25], off
	v_lshl_add_u64 v[24:25], v[72:73], 1, s[38:39]
	s_mov_b32 m0, s1
	v_ashrrev_i32_e32 v65, 31, v64
	v_readfirstlane_b32 s1, v28
	global_load_lds_dwordx4 v[24:25], off
	v_lshl_add_u64 v[24:25], v[64:65], 1, s[38:39]
	s_mov_b32 m0, s1
	v_bfe_u32 v29, v26, 1, 1
	global_load_lds_dwordx4 v[24:25], off
	v_bfe_u32 v24, v26, 4, 2
	v_bfe_u32 v25, v26, 2, 2
	v_xor_b32_e32 v28, v24, v25
	v_lshlrev_b32_e32 v25, 7, v25
	v_lshlrev_b32_e32 v30, 1, v24
	v_lshl_or_b32 v24, v24, 9, v25
	v_lshlrev_b32_e32 v25, 3, v26
	v_bfe_u32 v31, v26, 3, 1
	v_and_b32_e32 v25, 8, v25
	s_movk_i32 s1, 0x3000
	v_or3_b32 v24, v24, v25, s1
	v_bitop3_b32 v25, v30, v29, v31 bitop3:0x36
	v_lshl_or_b32 v77, v25, 4, v24
	v_or_b32_e32 v25, 2, v29
	v_bitop3_b32 v25, v30, v25, v31 bitop3:0x36
	v_lshl_or_b32 v78, v25, 4, v24
	v_or_b32_e32 v25, 4, v29
	v_bitop3_b32 v25, v30, v25, v31 bitop3:0x36
	v_lshl_or_b32 v79, v25, 4, v24
	v_or_b32_e32 v25, 6, v29
	v_bitop3_b32 v25, v30, v25, v31 bitop3:0x36
	v_lshl_or_b32 v80, v25, 4, v24
	v_mul_u32_u24_e32 v24, 0xc0, v27
	v_lshl_or_b32 v81, v28, 4, v24
	v_mov_b32_e32 v24, 0
	v_readlane_b32 s48, v255, 3
	s_mov_b32 s25, 0
	v_mov_b32_e32 v25, v24
	v_mov_b32_e32 v26, v24
	v_mov_b32_e32 v27, v24
	v_mov_b32_e32 v40, v24
	v_mov_b32_e32 v41, v24
	v_mov_b32_e32 v42, v24
	v_mov_b32_e32 v43, v24
	v_mov_b32_e32 v28, v24
	v_mov_b32_e32 v29, v24
	v_mov_b32_e32 v30, v24
	v_mov_b32_e32 v31, v24
	v_mov_b32_e32 v48, v24
	v_mov_b32_e32 v49, v24
	v_mov_b32_e32 v50, v24
	v_mov_b32_e32 v51, v24
	v_mov_b32_e32 v32, v24
	v_mov_b32_e32 v33, v24
	v_mov_b32_e32 v34, v24
	v_mov_b32_e32 v35, v24
	v_mov_b32_e32 v56, v24
	v_mov_b32_e32 v57, v24
	v_mov_b32_e32 v58, v24
	v_mov_b32_e32 v59, v24
	v_mov_b32_e32 v44, v24
	v_mov_b32_e32 v45, v24
	v_mov_b32_e32 v46, v24
	v_mov_b32_e32 v47, v24
	v_mov_b32_e32 v60, v24
	v_mov_b32_e32 v61, v24
	v_mov_b32_e32 v62, v24
	v_mov_b32_e32 v63, v24
	v_mov_b32_e32 v52, v24
	v_mov_b32_e32 v53, v24
	v_mov_b32_e32 v54, v24
	v_mov_b32_e32 v55, v24
	v_mov_b32_e32 v36, v24
	v_mov_b32_e32 v37, v24
	v_mov_b32_e32 v38, v24
	v_mov_b32_e32 v39, v24
	v_readlane_b32 s49, v255, 4
	v_readlane_b32 s50, v255, 5
	v_readlane_b32 s51, v255, 6
	s_waitcnt vmcnt(0)
	s_waitcnt lgkmcnt(0)
	s_barrier
	s_add_i32 s42, s41, -1
	s_min_u32 s28, 1, s42
	s_mul_i32 s42, s28, 0x18000
	s_mul_hi_u32 s25, s28, 0x18000
	s_add_u32 s42, s36, s42
	s_addc_u32 s43, s37, s25
	s_lshl_b64 s[44:45], s[28:29], 17
	s_add_u32 s44, s38, s44
	s_addc_u32 s45, s39, s45
	v_add_u32_e32 v128, 0x5000, v76
	s_nop 0
	v_readfirstlane_b32 s25, v128
	v_add_u32_e32 v131, 0x1000, v128
	ds_read_b128 v[154:157], v81 offset:0
	ds_read_b128 v[158:161], v81 offset:3072
	ds_read_b128 v[162:165], v81 offset:6144
	ds_read_b128 v[166:169], v81 offset:9216
	ds_read_b128 v[170:173], v81 offset:64
	ds_read_b128 v[174:177], v81 offset:3136
	ds_read_b128 v[178:181], v81 offset:6208
	ds_read_b128 v[182:185], v81 offset:9280
	ds_read_b128 v[186:189], v81 offset:128
	ds_read_b128 v[190:193], v81 offset:3200
	ds_read_b128 v[194:197], v81 offset:6272
	ds_read_b128 v[198:201], v81 offset:9344
	v_lshl_add_u64 v[126:127], v[66:67], 1, s[42:43]
	v_add_u32_e32 v133, 0x2000, v128
	v_readfirstlane_b32 s28, v131
	s_mov_b32 m0, s25
	v_lshl_add_u64 v[232:233], v[68:69], 1, s[42:43]
	v_lshl_add_u64 v[234:235], v[70:71], 1, s[42:43]
	v_add_u32_e32 v240, 0x3000, v128
	v_readfirstlane_b32 s42, v133
	global_load_lds_dwordx4 v[126:127], off
	s_mov_b32 m0, s28
	v_add_u32_e32 v128, 0x4000, v128
	v_readfirstlane_b32 s43, v240
	global_load_lds_dwordx4 v[232:233], off
	s_mov_b32 m0, s42
	v_lshl_add_u64 v[236:237], v[72:73], 1, s[44:45]
	v_lshl_add_u64 v[238:239], v[64:65], 1, s[44:45]
	v_readfirstlane_b32 s44, v128
	global_load_lds_dwordx4 v[234:235], off
	s_mov_b32 m0, s43
	s_nop 0
	global_load_lds_dwordx4 v[236:237], off
	s_mov_b32 m0, s44
	s_nop 0
	global_load_lds_dwordx4 v[238:239], off
	s_mov_b32 s25, 0
.LBB0_123:
	s_bitcmp1_b32 s25, 0
	s_cselect_b32 s26, 0x5000, 0
	s_add_i32 s1, s25, 1
	v_add_u32_e32 v126, s26, v77
	v_add_u32_e32 v127, s26, v78
	s_waitcnt lgkmcnt(8)
	v_add_u32_e32 v128, s26, v79
	v_mfma_f32_16x16x32_bf16 v[138:141], v[154:157], v[0:3], 0
	v_add_u32_e32 v131, s26, v80
	v_mfma_f32_16x16x32_bf16 v[82:85], v[154:157], v[12:15], 0
	v_mfma_f32_16x16x32_bf16 v[142:145], v[158:161], v[0:3], 0
	v_mfma_f32_16x16x32_bf16 v[86:89], v[158:161], v[12:15], 0
	v_mfma_f32_16x16x32_bf16 v[146:149], v[162:165], v[0:3], 0
	v_mfma_f32_16x16x32_bf16 v[90:93], v[162:165], v[12:15], 0
	s_waitcnt lgkmcnt(4)
	v_mfma_f32_16x16x32_bf16 v[150:153], v[166:169], v[0:3], 0
	v_mfma_f32_16x16x32_bf16 v[94:97], v[166:169], v[12:15], 0
	v_mfma_f32_16x16x32_bf16 v[138:141], v[170:173], v[4:7], v[138:141]
	v_mfma_f32_16x16x32_bf16 v[82:85], v[170:173], v[16:19], v[82:85]
	v_mfma_f32_16x16x32_bf16 v[98:101], v[174:177], v[4:7], v[142:145]
	v_mfma_f32_16x16x32_bf16 v[86:89], v[174:177], v[16:19], v[86:89]
	v_mfma_f32_16x16x32_bf16 v[90:93], v[178:181], v[16:19], v[90:93]
	s_waitcnt lgkmcnt(0)
	v_mfma_f32_16x16x32_bf16 v[102:105], v[178:181], v[4:7], v[146:149]
	v_mfma_f32_16x16x32_bf16 v[106:109], v[182:185], v[4:7], v[150:153]
	v_mfma_f32_16x16x32_bf16 v[94:97], v[182:185], v[16:19], v[94:97]
	v_mfma_f32_16x16x32_bf16 v[82:85], v[186:189], v[20:23], v[82:85]
	v_mfma_f32_16x16x32_bf16 v[98:101], v[190:193], v[8:11], v[98:101]
	v_mfma_f32_16x16x32_bf16 v[86:89], v[190:193], v[20:23], v[86:89]
	s_nop 5
	v_exp_f32_e32 v133, v82
	v_mfma_f32_16x16x32_bf16 v[106:109], v[198:201], v[8:11], v[106:109]
	v_mfma_f32_16x16x32_bf16 v[94:97], v[198:201], v[20:23], v[94:97]
	v_exp_f32_e32 v135, v84
	v_exp_f32_e32 v136, v85
	v_exp_f32_e32 v84, v98
	v_exp_f32_e32 v85, v99
	v_exp_f32_e32 v98, v100
	v_exp_f32_e32 v99, v101
	v_exp_f32_e32 v100, v86
	v_exp_f32_e32 v101, v87
	v_mfma_f32_16x16x32_bf16 v[110:113], v[186:189], v[8:11], v[138:141]
	v_exp_f32_e32 v137, v88
	v_cvt_pk_bf16_f32 v84, v84, v85
	v_cvt_pk_bf16_f32 v85, v98, v99
	v_cvt_pk_bf16_f32 v88, v100, v101
	v_mov_b64_e32 v[100:101], s[50:51]
	v_mfma_f32_16x16x32_bf16 v[102:105], v[194:197], v[8:11], v[102:105]
	s_nop 1
	v_exp_f32_e32 v110, v110
	v_exp_f32_e32 v111, v111
	v_exp_f32_e32 v112, v112
	v_mfma_f32_16x16x32_bf16 v[90:93], v[194:197], v[20:23], v[90:93]
	v_exp_f32_e32 v113, v113
	v_exp_f32_e32 v134, v83
	v_exp_f32_e32 v89, v89
	v_mov_b64_e32 v[98:99], s[48:49]
	ds_read_b64_tr_b16 v[138:139], v126 offset:0
	ds_read_b64_tr_b16 v[140:141], v126 offset:2048
	ds_read_b64_tr_b16 v[122:123], v127 offset:0
	ds_read_b64_tr_b16 v[124:125], v127 offset:2048
	ds_read_b64_tr_b16 v[118:119], v128 offset:0
	ds_read_b64_tr_b16 v[120:121], v128 offset:2048
	ds_read_b64_tr_b16 v[114:115], v131 offset:0
	ds_read_b64_tr_b16 v[116:117], v131 offset:2048
	v_cvt_pk_bf16_f32 v82, v110, v111
	v_cvt_pk_bf16_f32 v83, v112, v113
	v_cvt_pk_bf16_f32 v86, v133, v134
	v_cvt_pk_bf16_f32 v87, v135, v136
	v_cvt_pk_bf16_f32 v89, v137, v89
	v_exp_f32_e32 v102, v102
	v_exp_f32_e32 v103, v103
	v_exp_f32_e32 v104, v104
	v_exp_f32_e32 v105, v105
	v_exp_f32_e32 v90, v90
	v_exp_f32_e32 v91, v91
	v_exp_f32_e32 v92, v92
	v_exp_f32_e32 v93, v93
	v_exp_f32_e32 v106, v106
	v_exp_f32_e32 v107, v107
	v_exp_f32_e32 v108, v108
	v_exp_f32_e32 v109, v109
	v_exp_f32_e32 v94, v94
	v_exp_f32_e32 v95, v95
	v_exp_f32_e32 v96, v96
	v_exp_f32_e32 v97, v97
	s_waitcnt lgkmcnt(0)
	v_mfma_f32_16x16x32_bf16 v[52:55], v[98:101], v[82:85], v[52:55]
	v_mfma_f32_16x16x32_bf16 v[44:47], v[138:141], v[86:89], v[44:47]
	v_mfma_f32_16x16x32_bf16 v[56:59], v[122:125], v[82:85], v[56:59]
	v_mfma_f32_16x16x32_bf16 v[32:35], v[122:125], v[86:89], v[32:35]
	v_mfma_f32_16x16x32_bf16 v[48:51], v[118:121], v[82:85], v[48:51]
	v_mfma_f32_16x16x32_bf16 v[28:31], v[118:121], v[86:89], v[28:31]
	v_mfma_f32_16x16x32_bf16 v[40:43], v[114:117], v[82:85], v[40:43]
	v_mfma_f32_16x16x32_bf16 v[24:27], v[114:117], v[86:89], v[24:27]
	v_mfma_f32_16x16x32_bf16 v[36:39], v[98:101], v[86:89], v[36:39]
	v_cvt_pk_bf16_f32 v86, v90, v91
	v_cvt_pk_bf16_f32 v87, v92, v93
	v_cvt_pk_bf16_f32 v88, v94, v95
	v_mfma_f32_16x16x32_bf16 v[60:63], v[138:141], v[82:85], v[60:63]
	ds_read_b64_tr_b16 v[142:143], v126 offset:4096
	ds_read_b64_tr_b16 v[144:145], v126 offset:6144
	ds_read_b64_tr_b16 v[138:139], v127 offset:4096
	ds_read_b64_tr_b16 v[140:141], v127 offset:6144
	ds_read_b64_tr_b16 v[134:135], v128 offset:4096
	ds_read_b64_tr_b16 v[136:137], v128 offset:6144
	ds_read_b64_tr_b16 v[110:111], v131 offset:4096
	ds_read_b64_tr_b16 v[112:113], v131 offset:6144
	v_cvt_pk_bf16_f32 v82, v102, v103
	v_cvt_pk_bf16_f32 v83, v104, v105
	v_cvt_pk_bf16_f32 v84, v106, v107
	v_cvt_pk_bf16_f32 v85, v108, v109
	v_cvt_pk_bf16_f32 v89, v96, v97
	s_waitcnt lgkmcnt(0)
	s_add_i32 s28, s1, 1
	s_add_i32 s42, s41, -1
	s_min_u32 s28, s28, s42
	s_mul_i32 s42, s28, 0x18000
	s_mul_hi_u32 s25, s28, 0x18000
	s_add_u32 s42, s36, s42
	s_addc_u32 s43, s37, s25
	s_lshl_b64 s[44:45], s[28:29], 17
	s_add_u32 s44, s38, s44
	s_addc_u32 s45, s39, s45
	s_sub_i32 s28, 0x5000, s26
	s_waitcnt vmcnt(0)
	v_add_u32_e32 v128, s26, v76
	s_barrier
	v_or_b32_e32 v241, s28, v81
	v_readfirstlane_b32 s25, v128
	v_add_u32_e32 v131, 0x1000, v128
	ds_read_b128 v[154:157], v241 offset:0
	ds_read_b128 v[158:161], v241 offset:3072
	ds_read_b128 v[162:165], v241 offset:6144
	ds_read_b128 v[166:169], v241 offset:9216
	ds_read_b128 v[170:173], v241 offset:64
	ds_read_b128 v[174:177], v241 offset:3136
	ds_read_b128 v[178:181], v241 offset:6208
	ds_read_b128 v[182:185], v241 offset:9280
	ds_read_b128 v[186:189], v241 offset:128
	ds_read_b128 v[190:193], v241 offset:3200
	ds_read_b128 v[194:197], v241 offset:6272
	ds_read_b128 v[198:201], v241 offset:9344
	v_lshl_add_u64 v[126:127], v[66:67], 1, s[42:43]
	v_add_u32_e32 v133, 0x2000, v128
	v_readfirstlane_b32 s28, v131
	s_mov_b32 m0, s25
	v_lshl_add_u64 v[232:233], v[68:69], 1, s[42:43]
	v_lshl_add_u64 v[234:235], v[70:71], 1, s[42:43]
	v_add_u32_e32 v240, 0x3000, v128
	v_readfirstlane_b32 s42, v133
	global_load_lds_dwordx4 v[126:127], off
	s_mov_b32 m0, s28
	v_add_u32_e32 v128, 0x4000, v128
	v_readfirstlane_b32 s43, v240
	global_load_lds_dwordx4 v[232:233], off
	s_mov_b32 m0, s42
	v_lshl_add_u64 v[236:237], v[72:73], 1, s[44:45]
	v_lshl_add_u64 v[238:239], v[64:65], 1, s[44:45]
	v_readfirstlane_b32 s44, v128
	global_load_lds_dwordx4 v[234:235], off
	s_mov_b32 m0, s43
	s_nop 0
	global_load_lds_dwordx4 v[236:237], off
	s_mov_b32 m0, s44
	s_nop 0
	global_load_lds_dwordx4 v[238:239], off
	s_nop 0
	v_mfma_f32_16x16x32_bf16 v[52:55], v[98:101], v[82:85], v[52:55]
	v_mfma_f32_16x16x32_bf16 v[36:39], v[98:101], v[86:89], v[36:39]
	v_mfma_f32_16x16x32_bf16 v[60:63], v[142:145], v[82:85], v[60:63]
	v_mfma_f32_16x16x32_bf16 v[44:47], v[142:145], v[86:89], v[44:47]
	v_mfma_f32_16x16x32_bf16 v[56:59], v[138:141], v[82:85], v[56:59]
	v_mfma_f32_16x16x32_bf16 v[32:35], v[138:141], v[86:89], v[32:35]
	v_mfma_f32_16x16x32_bf16 v[48:51], v[134:137], v[82:85], v[48:51]
	v_mfma_f32_16x16x32_bf16 v[28:31], v[134:137], v[86:89], v[28:31]
	v_mfma_f32_16x16x32_bf16 v[40:43], v[110:113], v[82:85], v[40:43]
	v_mfma_f32_16x16x32_bf16 v[24:27], v[110:113], v[86:89], v[24:27]
	s_cmp_lg_u32 s41, s1
	s_mov_b32 s25, s1
	s_cbranch_scc1 .LBB0_123
	s_waitcnt lgkmcnt(0)
	v_div_scale_f32 v1, s[36:37], v52, v52, 1.0
	v_rcp_f32_e32 v2, v1
	v_ashrrev_i32_e32 v0, 1, v75
	v_and_b32_e32 v0, 0xffffffe0, v0
	v_add_u32_e32 v0, s0, v0
	v_and_or_b32 v12, v74, 15, v0
	v_fma_f32 v0, -v1, v2, 1.0
	v_fmac_f32_e32 v2, v0, v2
	v_div_scale_f32 v0, vcc, 1.0, v52, 1.0
	v_mul_f32_e32 v3, v0, v2
	v_fma_f32 v4, -v1, v3, v0
	v_fmac_f32_e32 v3, v4, v2
	v_fma_f32 v0, -v1, v3, v0
	v_div_fmas_f32 v0, v0, v2, v3
	v_mov_b64_e32 v[2:3], s[82:83]
	s_movk_i32 s1, 0xc00
	v_mad_i64_i32 v[4:5], s[36:37], v12, s1, v[2:3]
	v_lshrrev_b32_e32 v1, 1, v74
	v_lshl_add_u64 v[4:5], v[4:5], 0, s[30:31]
	v_and_b32_e32 v128, 24, v1
	v_div_fixup_f32 v0, v0, v52, 1.0
	v_lshl_add_u64 v[4:5], v[4:5], 0, v[128:129]
	s_mov_b64 s[38:39], 0xc65c400
	s_mov_b32 s25, 0xc65c000
	v_lshl_add_u64 v[6:7], v[4:5], 0, s[38:39]
	v_pk_mul_f32 v[8:9], v[60:61], v[0:1] op_sel_hi:[1,0]
	v_pk_mul_f32 v[10:11], v[62:63], v[0:1] op_sel_hi:[1,0]
	v_add_co_u32_e32 v4, vcc, s25, v4
	s_waitcnt vmcnt(0)
	v_cvt_pk_bf16_f32 v8, v8, v9
	v_cvt_pk_bf16_f32 v9, v10, v11
	v_addc_co_u32_e32 v5, vcc, 0, v5, vcc
	s_waitcnt lgkmcnt(0)
	s_barrier
	global_store_dwordx2 v[4:5], v[8:9], off offset:1024
	v_pk_mul_f32 v[4:5], v[56:57], v[0:1] op_sel_hi:[1,0]
	v_pk_mul_f32 v[8:9], v[58:59], v[0:1] op_sel_hi:[1,0]
	v_cvt_pk_bf16_f32 v4, v4, v5
	v_cvt_pk_bf16_f32 v5, v8, v9
	global_store_dwordx2 v[6:7], v[4:5], off offset:32
	v_pk_mul_f32 v[4:5], v[48:49], v[0:1] op_sel_hi:[1,0]
	v_pk_mul_f32 v[8:9], v[50:51], v[0:1] op_sel_hi:[1,0]
	v_cvt_pk_bf16_f32 v4, v4, v5
	v_cvt_pk_bf16_f32 v5, v8, v9
	v_div_scale_f32 v8, s[36:37], v36, v36, 1.0
	v_rcp_f32_e32 v9, v8
	global_store_dwordx2 v[6:7], v[4:5], off offset:64
	v_pk_mul_f32 v[4:5], v[40:41], v[0:1] op_sel_hi:[1,0]
	v_pk_mul_f32 v[0:1], v[42:43], v[0:1] op_sel_hi:[1,0]
	v_cvt_pk_bf16_f32 v4, v4, v5
	v_cvt_pk_bf16_f32 v5, v0, v1
	v_fma_f32 v0, -v8, v9, 1.0
	v_fmac_f32_e32 v9, v0, v9
	v_div_scale_f32 v0, vcc, 1.0, v36, 1.0
	v_mul_f32_e32 v1, v0, v9
	global_store_dwordx2 v[6:7], v[4:5], off offset:96
	v_fma_f32 v4, -v8, v1, v0
	v_fmac_f32_e32 v1, v4, v9
	v_fma_f32 v0, -v8, v1, v0
	v_div_fmas_f32 v0, v0, v9, v1
	v_or_b32_e32 v1, 16, v12
	v_mad_i64_i32 v[2:3], s[36:37], v1, s1, v[2:3]
	v_lshl_add_u64 v[2:3], v[2:3], 0, s[30:31]
	v_div_fixup_f32 v0, v0, v36, 1.0
	v_lshl_add_u64 v[2:3], v[2:3], 0, v[128:129]
	v_lshl_add_u64 v[4:5], v[2:3], 0, s[38:39]
	v_pk_mul_f32 v[6:7], v[44:45], v[0:1] op_sel_hi:[1,0]
	v_pk_mul_f32 v[8:9], v[46:47], v[0:1] op_sel_hi:[1,0]
	v_add_co_u32_e32 v2, vcc, s25, v2
	v_cvt_pk_bf16_f32 v6, v6, v7
	v_cvt_pk_bf16_f32 v7, v8, v9
	v_addc_co_u32_e32 v3, vcc, 0, v3, vcc
	global_store_dwordx2 v[2:3], v[6:7], off offset:1024
	v_pk_mul_f32 v[2:3], v[32:33], v[0:1] op_sel_hi:[1,0]
	v_pk_mul_f32 v[6:7], v[34:35], v[0:1] op_sel_hi:[1,0]
	v_cvt_pk_bf16_f32 v2, v2, v3
	v_cvt_pk_bf16_f32 v3, v6, v7
	global_store_dwordx2 v[4:5], v[2:3], off offset:32
	v_pk_mul_f32 v[2:3], v[28:29], v[0:1] op_sel_hi:[1,0]
	v_pk_mul_f32 v[6:7], v[30:31], v[0:1] op_sel_hi:[1,0]
	v_cvt_pk_bf16_f32 v2, v2, v3
	v_cvt_pk_bf16_f32 v3, v6, v7
	global_store_dwordx2 v[4:5], v[2:3], off offset:64
	v_pk_mul_f32 v[2:3], v[24:25], v[0:1] op_sel_hi:[1,0]
	v_pk_mul_f32 v[0:1], v[26:27], v[0:1] op_sel_hi:[1,0]
	s_movk_i32 s84, 0xc00
	v_cvt_pk_bf16_f32 v2, v2, v3
	v_cvt_pk_bf16_f32 v3, v0, v1
	v_readlane_b32 s92, v255, 31
	global_store_dwordx2 v[4:5], v[2:3], off offset:96
	v_readlane_b32 s93, v255, 32
	s_branch .LBB0_108
